# phase 0 keeps only the first-needed weight transposes (layer 0 W_in + GLU): all other tiles ride, in first-use order, in idle workgroups of both layers' w_in phases (third GEMM round) and behind the G
# speedup vs baseline: 1.0796x; 1.0449x over previous
.Lp0w_entry:
	s_cmpk_lt_u32 s63, 0x60
	s_cbranch_scc1 .LBB0_854
	s_add_u32 s38, s63, 216
	s_movk_i32 s56, 1272
	s_add_u32 s4, s63, 1688
	s_cmp_eq_u32 s36, 0
	s_cselect_b32 s38, s38, s4
	s_cselect_b32 s56, s56, 2744
	s_movk_i32 s39, 160
	s_branch .Lp0_common

.Lp0g_entry:
	s_cmpk_lt_u32 s63, 0xc0
	s_cbranch_scc1 .LBB0_854
	s_add_u32 s38, s63, 1080
	s_movk_i32 s56, 1784
	s_add_u32 s4, s63, 2552
	s_cmp_eq_u32 s36, 0
	s_cselect_b32 s38, s38, s4
	s_cselect_b32 s56, s56, 2928
	s_movk_i32 s39, 64
	s_branch .Lp0_common

.LBB0_182:
	s_andn2_b64 vcc, exec, s[38:39]
	s_cbranch_vccnz .LBB0_191
	s_branch .LBB0_191
.LBB0_191:
	s_mov_b64 s[38:39], 0

.LBB0_753:
	s_andn2_b64 vcc, exec, s[38:39]
	s_cbranch_vccnz .LBB0_763
	s_branch .LBB0_763
.LBB0_763:
	s_mov_b64 s[30:31], 0

.Lp0_start:
	s_waitcnt vmcnt(0) lgkmcnt(0)
	s_barrier
	s_cmp_eq_u32 s57, 1
	s_cbranch_scc1 .Lp0_common2
	v_readlane_b32 s38, v237, 0
	v_readlane_b32 s39, v235, 55
	s_movk_i32 s56, 0x138

.Lp0_cnt:
	s_add_u32 s37, s37, 1
	s_add_u32 s38, s38, s39
	s_cmp_lt_u32 s38, s56
	s_cbranch_scc1 .Lp0_cnt
	s_cmp_ge_u32 s36, s56
	s_cbranch_scc1 .Lp0_pro0
	s_cmpk_ge_u32 s36, 0x5b8
	s_cselect_b32 s4, 0x5b8, 0
	s_sub_u32 s5, s36, s4
	s_add_u32 s6, s5, 1152
	s_sub_u32 s7, s5, 8
	s_cmpk_lt_u32 s5, 0x138
	s_cselect_b32 s7, s6, s7
	s_cmpk_lt_u32 s5, 0x130
	s_cselect_b32 s7, s5, s7
	s_add_u32 s58, s7, s4
	s_cmpk_ge_u32 s58, 0x5b8
	s_cselect_b32 s30, 1, 0
	s_mul_i32 s4, s30, 0x5b8
	s_sub_u32 s31, s58, s4
	s_cmpk_lt_u32 s31, 0x130
	s_cbranch_scc1 .Lp0_dec0_win
	s_cmpk_lt_u32 s31, 0x1b0
	s_cbranch_scc1 .Lp0_dec0_wout
	s_cmpk_lt_u32 s31, 0x3b0
	s_cbranch_scc1 .Lp0_dec0_w1
	s_cmpk_lt_u32 s31, 0x5b0
	s_cbranch_scc1 .Lp0_dec0_w2
	s_sub_u32 s31, s31, 0x5b0
	s_lshr_b32 s34, s31, 2
	s_and_b32 s35, s31, 3
	v_readlane_b32 s6, v237, 51
	v_readlane_b32 s7, v237, 52
	s_mul_i32 s4, s30, 0x40000
	s_add_u32 s6, s6, s4
	s_addc_u32 s7, s7, 0
	s_add_u32 s44, s96, 0x2d80000
	s_addc_u32 s45, s97, 0
	s_mul_i32 s4, s30, 0x20000
	s_movk_i32 s42, 0x400
	s_movk_i32 s46, 0x200
	s_movk_i32 s5, 0x100
	s_branch .Lp0_dec0_join

.Lp0_pro0:
	s_cmp_ge_u32 s36, s56
	s_cbranch_scc1 .Lp0_pro1
	s_cmpk_ge_u32 s36, 0x5b8
	s_cselect_b32 s4, 0x5b8, 0
	s_sub_u32 s5, s36, s4
	s_add_u32 s6, s5, 1152
	s_sub_u32 s7, s5, 8
	s_cmpk_lt_u32 s5, 0x138
	s_cselect_b32 s7, s6, s7
	s_cmpk_lt_u32 s5, 0x130
	s_cselect_b32 s7, s5, s7
	s_add_u32 s58, s7, s4
	s_cmpk_ge_u32 s58, 0x5b8
	s_cselect_b32 s30, 1, 0
	s_mul_i32 s4, s30, 0x5b8
	s_sub_u32 s31, s58, s4
	s_cmpk_lt_u32 s31, 0x130
	s_cbranch_scc1 .Lp0_dec1_win
	s_cmpk_lt_u32 s31, 0x1b0
	s_cbranch_scc1 .Lp0_dec1_wout
	s_cmpk_lt_u32 s31, 0x3b0
	s_cbranch_scc1 .Lp0_dec1_w1
	s_cmpk_lt_u32 s31, 0x5b0
	s_cbranch_scc1 .Lp0_dec1_w2
	s_sub_u32 s31, s31, 0x5b0
	s_lshr_b32 s34, s31, 2
	s_and_b32 s35, s31, 3
	v_readlane_b32 s6, v237, 51
	v_readlane_b32 s7, v237, 52
	s_mul_i32 s4, s30, 0x40000
	s_add_u32 s6, s6, s4
	s_addc_u32 s7, s7, 0
	s_add_u32 s52, s96, 0x2d80000
	s_addc_u32 s53, s97, 0
	s_mul_i32 s4, s30, 0x20000
	s_movk_i32 s50, 0x400
	s_movk_i32 s54, 0x200
	s_movk_i32 s5, 0x100
	s_branch .Lp0_dec1_join

.Lp0_pro1:
	s_cmp_ge_u32 s36, s56
	s_cbranch_scc1 .Lp0_pro2
	s_cmpk_ge_u32 s36, 0x5b8
	s_cselect_b32 s4, 0x5b8, 0
	s_sub_u32 s5, s36, s4
	s_add_u32 s6, s5, 1152
	s_sub_u32 s7, s5, 8
	s_cmpk_lt_u32 s5, 0x138
	s_cselect_b32 s7, s6, s7
	s_cmpk_lt_u32 s5, 0x130
	s_cselect_b32 s7, s5, s7
	s_add_u32 s58, s7, s4
	s_cmpk_ge_u32 s58, 0x5b8
	s_cselect_b32 s30, 1, 0
	s_mul_i32 s4, s30, 0x5b8
	s_sub_u32 s31, s58, s4
	s_cmpk_lt_u32 s31, 0x130
	s_cbranch_scc1 .Lp0_dec2_win
	s_cmpk_lt_u32 s31, 0x1b0
	s_cbranch_scc1 .Lp0_dec2_wout
	s_cmpk_lt_u32 s31, 0x3b0
	s_cbranch_scc1 .Lp0_dec2_w1
	s_cmpk_lt_u32 s31, 0x5b0
	s_cbranch_scc1 .Lp0_dec2_w2
	s_sub_u32 s31, s31, 0x5b0
	s_lshr_b32 s34, s31, 2
	s_and_b32 s35, s31, 3
	v_readlane_b32 s6, v237, 51
	v_readlane_b32 s7, v237, 52
	s_mul_i32 s4, s30, 0x40000
	s_add_u32 s6, s6, s4
	s_addc_u32 s7, s7, 0
	s_add_u32 s12, s96, 0x2d80000
	s_addc_u32 s13, s97, 0
	s_mul_i32 s4, s30, 0x20000
	s_movk_i32 s10, 0x400
	s_movk_i32 s14, 0x200
	s_movk_i32 s5, 0x100
	s_branch .Lp0_dec2_join

.Lp0_w0:
	s_waitcnt vmcnt(8)
	ds_write2_b32 v6, v20, v21 offset1:1
	ds_write2_b32 v6, v22, v23 offset0:2 offset1:3
	ds_write2_b32 v7, v24, v25 offset1:1
	ds_write2_b32 v7, v26, v27 offset0:2 offset1:3
	ds_write2_b32 v8, v28, v29 offset1:1
	ds_write2_b32 v8, v30, v31 offset0:2 offset1:3
	ds_write2_b32 v9, v32, v33 offset1:1
	ds_write2_b32 v9, v34, v35 offset0:2 offset1:3
	s_waitcnt lgkmcnt(0)
	s_barrier
	v_mul_lo_u32 v13, v4, s46
	v_lshl_add_u32 v13, v5, 4, v13
	s_lshl_b32 s4, s46, 5
	ds_read_b32 v68, v10 offset:0
	ds_read_b32 v69, v10 offset:260
	ds_read_b32 v70, v10 offset:520
	ds_read_b32 v71, v10 offset:780
	ds_read_b32 v72, v10 offset:1040
	ds_read_b32 v73, v10 offset:1300
	ds_read_b32 v74, v10 offset:1560
	ds_read_b32 v75, v10 offset:1820
	s_waitcnt lgkmcnt(0)
	v_cvt_pk_bf16_f32 v84, v68, v69
	v_cvt_pk_bf16_f32 v85, v70, v71
	v_cvt_pk_bf16_f32 v86, v72, v73
	v_cvt_pk_bf16_f32 v87, v74, v75
	global_store_dwordx4 v13, v[84:87], s[44:45]
	v_add_u32_e32 v13, s4, v13
	ds_read_b32 v68, v11 offset:0
	ds_read_b32 v69, v11 offset:260
	ds_read_b32 v70, v11 offset:520
	ds_read_b32 v71, v11 offset:780
	ds_read_b32 v72, v11 offset:1040
	ds_read_b32 v73, v11 offset:1300
	ds_read_b32 v74, v11 offset:1560
	ds_read_b32 v75, v11 offset:1820
	s_waitcnt lgkmcnt(0)
	v_cvt_pk_bf16_f32 v88, v68, v69
	v_cvt_pk_bf16_f32 v89, v70, v71
	v_cvt_pk_bf16_f32 v90, v72, v73
	v_cvt_pk_bf16_f32 v91, v74, v75
	global_store_dwordx4 v13, v[88:91], s[44:45]
	s_cmp_ge_u32 s36, s56
	s_cbranch_scc1 .Lp0_r0
	s_cmpk_ge_u32 s36, 0x5b8
	s_cselect_b32 s4, 0x5b8, 0
	s_sub_u32 s5, s36, s4
	s_add_u32 s6, s5, 1152
	s_sub_u32 s7, s5, 8
	s_cmpk_lt_u32 s5, 0x138
	s_cselect_b32 s7, s6, s7
	s_cmpk_lt_u32 s5, 0x130
	s_cselect_b32 s7, s5, s7
	s_add_u32 s58, s7, s4
	s_cmpk_ge_u32 s58, 0x5b8
	s_cselect_b32 s30, 1, 0
	s_mul_i32 s4, s30, 0x5b8
	s_sub_u32 s31, s58, s4
	s_cmpk_lt_u32 s31, 0x130
	s_cbranch_scc1 .Lp0_dec3_win
	s_cmpk_lt_u32 s31, 0x1b0
	s_cbranch_scc1 .Lp0_dec3_wout
	s_cmpk_lt_u32 s31, 0x3b0
	s_cbranch_scc1 .Lp0_dec3_w1
	s_cmpk_lt_u32 s31, 0x5b0
	s_cbranch_scc1 .Lp0_dec3_w2
	s_sub_u32 s31, s31, 0x5b0
	s_lshr_b32 s34, s31, 2
	s_and_b32 s35, s31, 3
	v_readlane_b32 s6, v237, 51
	v_readlane_b32 s7, v237, 52
	s_mul_i32 s4, s30, 0x40000
	s_add_u32 s6, s6, s4
	s_addc_u32 s7, s7, 0
	s_add_u32 s44, s96, 0x2d80000
	s_addc_u32 s45, s97, 0
	s_mul_i32 s4, s30, 0x20000
	s_movk_i32 s42, 0x400
	s_movk_i32 s46, 0x200
	s_movk_i32 s5, 0x100
	s_branch .Lp0_dec3_join

.Lp0_w1:
	s_waitcnt vmcnt(10)
	v_add_u32_e32 v68, 0x8200, v6
	ds_write2_b32 v68, v36, v37 offset1:1
	ds_write2_b32 v68, v38, v39 offset0:2 offset1:3
	v_add_u32_e32 v68, 0x8200, v7
	ds_write2_b32 v68, v40, v41 offset1:1
	ds_write2_b32 v68, v42, v43 offset0:2 offset1:3
	v_add_u32_e32 v68, 0x8200, v8
	ds_write2_b32 v68, v44, v45 offset1:1
	ds_write2_b32 v68, v46, v47 offset0:2 offset1:3
	v_add_u32_e32 v68, 0x8200, v9
	ds_write2_b32 v68, v48, v49 offset1:1
	ds_write2_b32 v68, v50, v51 offset0:2 offset1:3
	s_waitcnt lgkmcnt(0)
	s_barrier
	v_mul_lo_u32 v13, v4, s54
	v_lshl_add_u32 v13, v5, 4, v13
	s_lshl_b32 s4, s54, 5
	v_add_u32_e32 v83, 0x8200, v10
	ds_read_b32 v68, v83 offset:0
	ds_read_b32 v69, v83 offset:260
	ds_read_b32 v70, v83 offset:520
	ds_read_b32 v71, v83 offset:780
	ds_read_b32 v72, v83 offset:1040
	ds_read_b32 v73, v83 offset:1300
	ds_read_b32 v74, v83 offset:1560
	ds_read_b32 v75, v83 offset:1820
	s_waitcnt lgkmcnt(0)
	v_cvt_pk_bf16_f32 v84, v68, v69
	v_cvt_pk_bf16_f32 v85, v70, v71
	v_cvt_pk_bf16_f32 v86, v72, v73
	v_cvt_pk_bf16_f32 v87, v74, v75
	global_store_dwordx4 v13, v[84:87], s[52:53]
	v_add_u32_e32 v13, s4, v13
	v_add_u32_e32 v83, 0x8200, v11
	ds_read_b32 v68, v83 offset:0
	ds_read_b32 v69, v83 offset:260
	ds_read_b32 v70, v83 offset:520
	ds_read_b32 v71, v83 offset:780
	ds_read_b32 v72, v83 offset:1040
	ds_read_b32 v73, v83 offset:1300
	ds_read_b32 v74, v83 offset:1560
	ds_read_b32 v75, v83 offset:1820
	s_waitcnt lgkmcnt(0)
	v_cvt_pk_bf16_f32 v88, v68, v69
	v_cvt_pk_bf16_f32 v89, v70, v71
	v_cvt_pk_bf16_f32 v90, v72, v73
	v_cvt_pk_bf16_f32 v91, v74, v75
	global_store_dwordx4 v13, v[88:91], s[52:53]
	s_cmp_ge_u32 s36, s56
	s_cbranch_scc1 .Lp0_r1
	s_cmpk_ge_u32 s36, 0x5b8
	s_cselect_b32 s4, 0x5b8, 0
	s_sub_u32 s5, s36, s4
	s_add_u32 s6, s5, 1152
	s_sub_u32 s7, s5, 8
	s_cmpk_lt_u32 s5, 0x138
	s_cselect_b32 s7, s6, s7
	s_cmpk_lt_u32 s5, 0x130
	s_cselect_b32 s7, s5, s7
	s_add_u32 s58, s7, s4
	s_cmpk_ge_u32 s58, 0x5b8
	s_cselect_b32 s30, 1, 0
	s_mul_i32 s4, s30, 0x5b8
	s_sub_u32 s31, s58, s4
	s_cmpk_lt_u32 s31, 0x130
	s_cbranch_scc1 .Lp0_dec4_win
	s_cmpk_lt_u32 s31, 0x1b0
	s_cbranch_scc1 .Lp0_dec4_wout
	s_cmpk_lt_u32 s31, 0x3b0
	s_cbranch_scc1 .Lp0_dec4_w1
	s_cmpk_lt_u32 s31, 0x5b0
	s_cbranch_scc1 .Lp0_dec4_w2
	s_sub_u32 s31, s31, 0x5b0
	s_lshr_b32 s34, s31, 2
	s_and_b32 s35, s31, 3
	v_readlane_b32 s6, v237, 51
	v_readlane_b32 s7, v237, 52
	s_mul_i32 s4, s30, 0x40000
	s_add_u32 s6, s6, s4
	s_addc_u32 s7, s7, 0
	s_add_u32 s52, s96, 0x2d80000
	s_addc_u32 s53, s97, 0
	s_mul_i32 s4, s30, 0x20000
	s_movk_i32 s50, 0x400
	s_movk_i32 s54, 0x200
	s_movk_i32 s5, 0x100
	s_branch .Lp0_dec4_join

.Lp0_w2:
	s_waitcnt vmcnt(12)
	ds_write2_b32 v6, v52, v53 offset1:1
	ds_write2_b32 v6, v54, v55 offset0:2 offset1:3
	ds_write2_b32 v7, v56, v57 offset1:1
	ds_write2_b32 v7, v58, v59 offset0:2 offset1:3
	ds_write2_b32 v8, v60, v61 offset1:1
	ds_write2_b32 v8, v62, v63 offset0:2 offset1:3
	ds_write2_b32 v9, v64, v65 offset1:1
	ds_write2_b32 v9, v66, v67 offset0:2 offset1:3
	s_waitcnt lgkmcnt(0)
	s_barrier
	v_mul_lo_u32 v13, v4, s14
	v_lshl_add_u32 v13, v5, 4, v13
	s_lshl_b32 s4, s14, 5
	ds_read_b32 v68, v10 offset:0
	ds_read_b32 v69, v10 offset:260
	ds_read_b32 v70, v10 offset:520
	ds_read_b32 v71, v10 offset:780
	ds_read_b32 v72, v10 offset:1040
	ds_read_b32 v73, v10 offset:1300
	ds_read_b32 v74, v10 offset:1560
	ds_read_b32 v75, v10 offset:1820
	s_waitcnt lgkmcnt(0)
	v_cvt_pk_bf16_f32 v84, v68, v69
	v_cvt_pk_bf16_f32 v85, v70, v71
	v_cvt_pk_bf16_f32 v86, v72, v73
	v_cvt_pk_bf16_f32 v87, v74, v75
	global_store_dwordx4 v13, v[84:87], s[12:13]
	v_add_u32_e32 v13, s4, v13
	ds_read_b32 v68, v11 offset:0
	ds_read_b32 v69, v11 offset:260
	ds_read_b32 v70, v11 offset:520
	ds_read_b32 v71, v11 offset:780
	ds_read_b32 v72, v11 offset:1040
	ds_read_b32 v73, v11 offset:1300
	ds_read_b32 v74, v11 offset:1560
	ds_read_b32 v75, v11 offset:1820
	s_waitcnt lgkmcnt(0)
	v_cvt_pk_bf16_f32 v88, v68, v69
	v_cvt_pk_bf16_f32 v89, v70, v71
	v_cvt_pk_bf16_f32 v90, v72, v73
	v_cvt_pk_bf16_f32 v91, v74, v75
	global_store_dwordx4 v13, v[88:91], s[12:13]
	s_cmp_ge_u32 s36, s56
	s_cbranch_scc1 .Lp0_r2
	s_cmpk_ge_u32 s36, 0x5b8
	s_cselect_b32 s4, 0x5b8, 0
	s_sub_u32 s5, s36, s4
	s_add_u32 s6, s5, 1152
	s_sub_u32 s7, s5, 8
	s_cmpk_lt_u32 s5, 0x138
	s_cselect_b32 s7, s6, s7
	s_cmpk_lt_u32 s5, 0x130
	s_cselect_b32 s7, s5, s7
	s_add_u32 s58, s7, s4
	s_cmpk_ge_u32 s58, 0x5b8
	s_cselect_b32 s30, 1, 0
	s_mul_i32 s4, s30, 0x5b8
	s_sub_u32 s31, s58, s4
	s_cmpk_lt_u32 s31, 0x130
	s_cbranch_scc1 .Lp0_dec5_win
	s_cmpk_lt_u32 s31, 0x1b0
	s_cbranch_scc1 .Lp0_dec5_wout
	s_cmpk_lt_u32 s31, 0x3b0
	s_cbranch_scc1 .Lp0_dec5_w1
	s_cmpk_lt_u32 s31, 0x5b0
	s_cbranch_scc1 .Lp0_dec5_w2
	s_sub_u32 s31, s31, 0x5b0
	s_lshr_b32 s34, s31, 2
	s_and_b32 s35, s31, 3
	v_readlane_b32 s6, v237, 51
	v_readlane_b32 s7, v237, 52
	s_mul_i32 s4, s30, 0x40000
	s_add_u32 s6, s6, s4
	s_addc_u32 s7, s7, 0
	s_add_u32 s12, s96, 0x2d80000
	s_addc_u32 s13, s97, 0
	s_mul_i32 s4, s30, 0x20000
	s_movk_i32 s10, 0x400
	s_movk_i32 s14, 0x200
	s_movk_i32 s5, 0x100
	s_branch .Lp0_dec5_join

.Lp0_w3:
	s_waitcnt vmcnt(12)
	v_add_u32_e32 v68, 0x8200, v6
	ds_write2_b32 v68, v20, v21 offset1:1
	ds_write2_b32 v68, v22, v23 offset0:2 offset1:3
	v_add_u32_e32 v68, 0x8200, v7
	ds_write2_b32 v68, v24, v25 offset1:1
	ds_write2_b32 v68, v26, v27 offset0:2 offset1:3
	v_add_u32_e32 v68, 0x8200, v8
	ds_write2_b32 v68, v28, v29 offset1:1
	ds_write2_b32 v68, v30, v31 offset0:2 offset1:3
	v_add_u32_e32 v68, 0x8200, v9
	ds_write2_b32 v68, v32, v33 offset1:1
	ds_write2_b32 v68, v34, v35 offset0:2 offset1:3
	s_waitcnt lgkmcnt(0)
	s_barrier
	v_mul_lo_u32 v13, v4, s46
	v_lshl_add_u32 v13, v5, 4, v13
	s_lshl_b32 s4, s46, 5
	v_add_u32_e32 v83, 0x8200, v10
	ds_read_b32 v68, v83 offset:0
	ds_read_b32 v69, v83 offset:260
	ds_read_b32 v70, v83 offset:520
	ds_read_b32 v71, v83 offset:780
	ds_read_b32 v72, v83 offset:1040
	ds_read_b32 v73, v83 offset:1300
	ds_read_b32 v74, v83 offset:1560
	ds_read_b32 v75, v83 offset:1820
	s_waitcnt lgkmcnt(0)
	v_cvt_pk_bf16_f32 v84, v68, v69
	v_cvt_pk_bf16_f32 v85, v70, v71
	v_cvt_pk_bf16_f32 v86, v72, v73
	v_cvt_pk_bf16_f32 v87, v74, v75
	global_store_dwordx4 v13, v[84:87], s[44:45]
	v_add_u32_e32 v13, s4, v13
	v_add_u32_e32 v83, 0x8200, v11
	ds_read_b32 v68, v83 offset:0
	ds_read_b32 v69, v83 offset:260
	ds_read_b32 v70, v83 offset:520
	ds_read_b32 v71, v83 offset:780
	ds_read_b32 v72, v83 offset:1040
	ds_read_b32 v73, v83 offset:1300
	ds_read_b32 v74, v83 offset:1560
	ds_read_b32 v75, v83 offset:1820
	s_waitcnt lgkmcnt(0)
	v_cvt_pk_bf16_f32 v88, v68, v69
	v_cvt_pk_bf16_f32 v89, v70, v71
	v_cvt_pk_bf16_f32 v90, v72, v73
	v_cvt_pk_bf16_f32 v91, v74, v75
	global_store_dwordx4 v13, v[88:91], s[44:45]
	s_cmp_ge_u32 s36, s56
	s_cbranch_scc1 .Lp0_r3
	s_cmpk_ge_u32 s36, 0x5b8
	s_cselect_b32 s4, 0x5b8, 0
	s_sub_u32 s5, s36, s4
	s_add_u32 s6, s5, 1152
	s_sub_u32 s7, s5, 8
	s_cmpk_lt_u32 s5, 0x138
	s_cselect_b32 s7, s6, s7
	s_cmpk_lt_u32 s5, 0x130
	s_cselect_b32 s7, s5, s7
	s_add_u32 s58, s7, s4
	s_cmpk_ge_u32 s58, 0x5b8
	s_cselect_b32 s30, 1, 0
	s_mul_i32 s4, s30, 0x5b8
	s_sub_u32 s31, s58, s4
	s_cmpk_lt_u32 s31, 0x130
	s_cbranch_scc1 .Lp0_dec6_win
	s_cmpk_lt_u32 s31, 0x1b0
	s_cbranch_scc1 .Lp0_dec6_wout
	s_cmpk_lt_u32 s31, 0x3b0
	s_cbranch_scc1 .Lp0_dec6_w1
	s_cmpk_lt_u32 s31, 0x5b0
	s_cbranch_scc1 .Lp0_dec6_w2
	s_sub_u32 s31, s31, 0x5b0
	s_lshr_b32 s34, s31, 2
	s_and_b32 s35, s31, 3
	v_readlane_b32 s6, v237, 51
	v_readlane_b32 s7, v237, 52
	s_mul_i32 s4, s30, 0x40000
	s_add_u32 s6, s6, s4
	s_addc_u32 s7, s7, 0
	s_add_u32 s44, s96, 0x2d80000
	s_addc_u32 s45, s97, 0
	s_mul_i32 s4, s30, 0x20000
	s_movk_i32 s42, 0x400
	s_movk_i32 s46, 0x200
	s_movk_i32 s5, 0x100
	s_branch .Lp0_dec6_join

.Lp0_w4:
	s_waitcnt vmcnt(12)
	ds_write2_b32 v6, v36, v37 offset1:1
	ds_write2_b32 v6, v38, v39 offset0:2 offset1:3
	ds_write2_b32 v7, v40, v41 offset1:1
	ds_write2_b32 v7, v42, v43 offset0:2 offset1:3
	ds_write2_b32 v8, v44, v45 offset1:1
	ds_write2_b32 v8, v46, v47 offset0:2 offset1:3
	ds_write2_b32 v9, v48, v49 offset1:1
	ds_write2_b32 v9, v50, v51 offset0:2 offset1:3
	s_waitcnt lgkmcnt(0)
	s_barrier
	v_mul_lo_u32 v13, v4, s54
	v_lshl_add_u32 v13, v5, 4, v13
	s_lshl_b32 s4, s54, 5
	ds_read_b32 v68, v10 offset:0
	ds_read_b32 v69, v10 offset:260
	ds_read_b32 v70, v10 offset:520
	ds_read_b32 v71, v10 offset:780
	ds_read_b32 v72, v10 offset:1040
	ds_read_b32 v73, v10 offset:1300
	ds_read_b32 v74, v10 offset:1560
	ds_read_b32 v75, v10 offset:1820
	s_waitcnt lgkmcnt(0)
	v_cvt_pk_bf16_f32 v84, v68, v69
	v_cvt_pk_bf16_f32 v85, v70, v71
	v_cvt_pk_bf16_f32 v86, v72, v73
	v_cvt_pk_bf16_f32 v87, v74, v75
	global_store_dwordx4 v13, v[84:87], s[52:53]
	v_add_u32_e32 v13, s4, v13
	ds_read_b32 v68, v11 offset:0
	ds_read_b32 v69, v11 offset:260
	ds_read_b32 v70, v11 offset:520
	ds_read_b32 v71, v11 offset:780
	ds_read_b32 v72, v11 offset:1040
	ds_read_b32 v73, v11 offset:1300
	ds_read_b32 v74, v11 offset:1560
	ds_read_b32 v75, v11 offset:1820
	s_waitcnt lgkmcnt(0)
	v_cvt_pk_bf16_f32 v88, v68, v69
	v_cvt_pk_bf16_f32 v89, v70, v71
	v_cvt_pk_bf16_f32 v90, v72, v73
	v_cvt_pk_bf16_f32 v91, v74, v75
	global_store_dwordx4 v13, v[88:91], s[52:53]
	s_cmp_ge_u32 s36, s56
	s_cbranch_scc1 .Lp0_r4
	s_cmpk_ge_u32 s36, 0x5b8
	s_cselect_b32 s4, 0x5b8, 0
	s_sub_u32 s5, s36, s4
	s_add_u32 s6, s5, 1152
	s_sub_u32 s7, s5, 8
	s_cmpk_lt_u32 s5, 0x138
	s_cselect_b32 s7, s6, s7
	s_cmpk_lt_u32 s5, 0x130
	s_cselect_b32 s7, s5, s7
	s_add_u32 s58, s7, s4
	s_cmpk_ge_u32 s58, 0x5b8
	s_cselect_b32 s30, 1, 0
	s_mul_i32 s4, s30, 0x5b8
	s_sub_u32 s31, s58, s4
	s_cmpk_lt_u32 s31, 0x130
	s_cbranch_scc1 .Lp0_dec7_win
	s_cmpk_lt_u32 s31, 0x1b0
	s_cbranch_scc1 .Lp0_dec7_wout
	s_cmpk_lt_u32 s31, 0x3b0
	s_cbranch_scc1 .Lp0_dec7_w1
	s_cmpk_lt_u32 s31, 0x5b0
	s_cbranch_scc1 .Lp0_dec7_w2
	s_sub_u32 s31, s31, 0x5b0
	s_lshr_b32 s34, s31, 2
	s_and_b32 s35, s31, 3
	v_readlane_b32 s6, v237, 51
	v_readlane_b32 s7, v237, 52
	s_mul_i32 s4, s30, 0x40000
	s_add_u32 s6, s6, s4
	s_addc_u32 s7, s7, 0
	s_add_u32 s52, s96, 0x2d80000
	s_addc_u32 s53, s97, 0
	s_mul_i32 s4, s30, 0x20000
	s_movk_i32 s50, 0x400
	s_movk_i32 s54, 0x200
	s_movk_i32 s5, 0x100
	s_branch .Lp0_dec7_join

.Lp0_w5:
	s_waitcnt vmcnt(12)
	v_add_u32_e32 v68, 0x8200, v6
	ds_write2_b32 v68, v52, v53 offset1:1
	ds_write2_b32 v68, v54, v55 offset0:2 offset1:3
	v_add_u32_e32 v68, 0x8200, v7
	ds_write2_b32 v68, v56, v57 offset1:1
	ds_write2_b32 v68, v58, v59 offset0:2 offset1:3
	v_add_u32_e32 v68, 0x8200, v8
	ds_write2_b32 v68, v60, v61 offset1:1
	ds_write2_b32 v68, v62, v63 offset0:2 offset1:3
	v_add_u32_e32 v68, 0x8200, v9
	ds_write2_b32 v68, v64, v65 offset1:1
	ds_write2_b32 v68, v66, v67 offset0:2 offset1:3
	s_waitcnt lgkmcnt(0)
	s_barrier
	v_mul_lo_u32 v13, v4, s14
	v_lshl_add_u32 v13, v5, 4, v13
	s_lshl_b32 s4, s14, 5
	v_add_u32_e32 v83, 0x8200, v10
	ds_read_b32 v68, v83 offset:0
	ds_read_b32 v69, v83 offset:260
	ds_read_b32 v70, v83 offset:520
	ds_read_b32 v71, v83 offset:780
	ds_read_b32 v72, v83 offset:1040
	ds_read_b32 v73, v83 offset:1300
	ds_read_b32 v74, v83 offset:1560
	ds_read_b32 v75, v83 offset:1820
	s_waitcnt lgkmcnt(0)
	v_cvt_pk_bf16_f32 v84, v68, v69
	v_cvt_pk_bf16_f32 v85, v70, v71
	v_cvt_pk_bf16_f32 v86, v72, v73
	v_cvt_pk_bf16_f32 v87, v74, v75
	global_store_dwordx4 v13, v[84:87], s[12:13]
	v_add_u32_e32 v13, s4, v13
	v_add_u32_e32 v83, 0x8200, v11
	ds_read_b32 v68, v83 offset:0
	ds_read_b32 v69, v83 offset:260
	ds_read_b32 v70, v83 offset:520
	ds_read_b32 v71, v83 offset:780
	ds_read_b32 v72, v83 offset:1040
	ds_read_b32 v73, v83 offset:1300
	ds_read_b32 v74, v83 offset:1560
	ds_read_b32 v75, v83 offset:1820
	s_waitcnt lgkmcnt(0)
	v_cvt_pk_bf16_f32 v88, v68, v69
	v_cvt_pk_bf16_f32 v89, v70, v71
	v_cvt_pk_bf16_f32 v90, v72, v73
	v_cvt_pk_bf16_f32 v91, v74, v75
	global_store_dwordx4 v13, v[88:91], s[12:13]
	s_cmp_ge_u32 s36, s56
	s_cbranch_scc1 .Lp0_r5
	s_cmpk_ge_u32 s36, 0x5b8
	s_cselect_b32 s4, 0x5b8, 0
	s_sub_u32 s5, s36, s4
	s_add_u32 s6, s5, 1152
	s_sub_u32 s7, s5, 8
	s_cmpk_lt_u32 s5, 0x138
	s_cselect_b32 s7, s6, s7
	s_cmpk_lt_u32 s5, 0x130
	s_cselect_b32 s7, s5, s7
	s_add_u32 s58, s7, s4
	s_cmpk_ge_u32 s58, 0x5b8
	s_cselect_b32 s30, 1, 0
	s_mul_i32 s4, s30, 0x5b8
	s_sub_u32 s31, s58, s4
	s_cmpk_lt_u32 s31, 0x130
	s_cbranch_scc1 .Lp0_dec8_win
	s_cmpk_lt_u32 s31, 0x1b0
	s_cbranch_scc1 .Lp0_dec8_wout
	s_cmpk_lt_u32 s31, 0x3b0
	s_cbranch_scc1 .Lp0_dec8_w1
	s_cmpk_lt_u32 s31, 0x5b0
	s_cbranch_scc1 .Lp0_dec8_w2
	s_sub_u32 s31, s31, 0x5b0
	s_lshr_b32 s34, s31, 2
	s_and_b32 s35, s31, 3
	v_readlane_b32 s6, v237, 51
	v_readlane_b32 s7, v237, 52
	s_mul_i32 s4, s30, 0x40000
	s_add_u32 s6, s6, s4
	s_addc_u32 s7, s7, 0
	s_add_u32 s12, s96, 0x2d80000
	s_addc_u32 s13, s97, 0
	s_mul_i32 s4, s30, 0x20000
	s_movk_i32 s10, 0x400
	s_movk_i32 s14, 0x200
	s_movk_i32 s5, 0x100
	s_branch .Lp0_dec8_join

.Lp0_w6:
	s_waitcnt vmcnt(12)
	ds_write2_b32 v6, v20, v21 offset1:1
	ds_write2_b32 v6, v22, v23 offset0:2 offset1:3
	ds_write2_b32 v7, v24, v25 offset1:1
	ds_write2_b32 v7, v26, v27 offset0:2 offset1:3
	ds_write2_b32 v8, v28, v29 offset1:1
	ds_write2_b32 v8, v30, v31 offset0:2 offset1:3
	ds_write2_b32 v9, v32, v33 offset1:1
	ds_write2_b32 v9, v34, v35 offset0:2 offset1:3
	s_waitcnt lgkmcnt(0)
	s_barrier
	v_mul_lo_u32 v13, v4, s46
	v_lshl_add_u32 v13, v5, 4, v13
	s_lshl_b32 s4, s46, 5
	ds_read_b32 v68, v10 offset:0
	ds_read_b32 v69, v10 offset:260
	ds_read_b32 v70, v10 offset:520
	ds_read_b32 v71, v10 offset:780
	ds_read_b32 v72, v10 offset:1040
	ds_read_b32 v73, v10 offset:1300
	ds_read_b32 v74, v10 offset:1560
	ds_read_b32 v75, v10 offset:1820
	s_waitcnt lgkmcnt(0)
	v_cvt_pk_bf16_f32 v84, v68, v69
	v_cvt_pk_bf16_f32 v85, v70, v71
	v_cvt_pk_bf16_f32 v86, v72, v73
	v_cvt_pk_bf16_f32 v87, v74, v75
	global_store_dwordx4 v13, v[84:87], s[44:45]
	v_add_u32_e32 v13, s4, v13
	ds_read_b32 v68, v11 offset:0
	ds_read_b32 v69, v11 offset:260
	ds_read_b32 v70, v11 offset:520
	ds_read_b32 v71, v11 offset:780
	ds_read_b32 v72, v11 offset:1040
	ds_read_b32 v73, v11 offset:1300
	ds_read_b32 v74, v11 offset:1560
	ds_read_b32 v75, v11 offset:1820
	s_waitcnt lgkmcnt(0)
	v_cvt_pk_bf16_f32 v88, v68, v69
	v_cvt_pk_bf16_f32 v89, v70, v71
	v_cvt_pk_bf16_f32 v90, v72, v73
	v_cvt_pk_bf16_f32 v91, v74, v75
	global_store_dwordx4 v13, v[88:91], s[44:45]
	s_cmp_ge_u32 s36, s56
	s_cbranch_scc1 .Lp0_r6
	s_cmpk_ge_u32 s36, 0x5b8
	s_cselect_b32 s4, 0x5b8, 0
	s_sub_u32 s5, s36, s4
	s_add_u32 s6, s5, 1152
	s_sub_u32 s7, s5, 8
	s_cmpk_lt_u32 s5, 0x138
	s_cselect_b32 s7, s6, s7
	s_cmpk_lt_u32 s5, 0x130
	s_cselect_b32 s7, s5, s7
	s_add_u32 s58, s7, s4
	s_cmpk_ge_u32 s58, 0x5b8
	s_cselect_b32 s30, 1, 0
	s_mul_i32 s4, s30, 0x5b8
	s_sub_u32 s31, s58, s4
	s_cmpk_lt_u32 s31, 0x130
	s_cbranch_scc1 .Lp0_dec9_win
	s_cmpk_lt_u32 s31, 0x1b0
	s_cbranch_scc1 .Lp0_dec9_wout
	s_cmpk_lt_u32 s31, 0x3b0
	s_cbranch_scc1 .Lp0_dec9_w1
	s_cmpk_lt_u32 s31, 0x5b0
	s_cbranch_scc1 .Lp0_dec9_w2
	s_sub_u32 s31, s31, 0x5b0
	s_lshr_b32 s34, s31, 2
	s_and_b32 s35, s31, 3
	v_readlane_b32 s6, v237, 51
	v_readlane_b32 s7, v237, 52
	s_mul_i32 s4, s30, 0x40000
	s_add_u32 s6, s6, s4
	s_addc_u32 s7, s7, 0
	s_add_u32 s44, s96, 0x2d80000
	s_addc_u32 s45, s97, 0
	s_mul_i32 s4, s30, 0x20000
	s_movk_i32 s42, 0x400
	s_movk_i32 s46, 0x200
	s_movk_i32 s5, 0x100
	s_branch .Lp0_dec9_join

.Lp0_w7:
	s_waitcnt vmcnt(12)
	v_add_u32_e32 v68, 0x8200, v6
	ds_write2_b32 v68, v36, v37 offset1:1
	ds_write2_b32 v68, v38, v39 offset0:2 offset1:3
	v_add_u32_e32 v68, 0x8200, v7
	ds_write2_b32 v68, v40, v41 offset1:1
	ds_write2_b32 v68, v42, v43 offset0:2 offset1:3
	v_add_u32_e32 v68, 0x8200, v8
	ds_write2_b32 v68, v44, v45 offset1:1
	ds_write2_b32 v68, v46, v47 offset0:2 offset1:3
	v_add_u32_e32 v68, 0x8200, v9
	ds_write2_b32 v68, v48, v49 offset1:1
	ds_write2_b32 v68, v50, v51 offset0:2 offset1:3
	s_waitcnt lgkmcnt(0)
	s_barrier
	v_mul_lo_u32 v13, v4, s54
	v_lshl_add_u32 v13, v5, 4, v13
	s_lshl_b32 s4, s54, 5
	v_add_u32_e32 v83, 0x8200, v10
	ds_read_b32 v68, v83 offset:0
	ds_read_b32 v69, v83 offset:260
	ds_read_b32 v70, v83 offset:520
	ds_read_b32 v71, v83 offset:780
	ds_read_b32 v72, v83 offset:1040
	ds_read_b32 v73, v83 offset:1300
	ds_read_b32 v74, v83 offset:1560
	ds_read_b32 v75, v83 offset:1820
	s_waitcnt lgkmcnt(0)
	v_cvt_pk_bf16_f32 v84, v68, v69
	v_cvt_pk_bf16_f32 v85, v70, v71
	v_cvt_pk_bf16_f32 v86, v72, v73
	v_cvt_pk_bf16_f32 v87, v74, v75
	global_store_dwordx4 v13, v[84:87], s[52:53]
	v_add_u32_e32 v13, s4, v13
	v_add_u32_e32 v83, 0x8200, v11
	ds_read_b32 v68, v83 offset:0
	ds_read_b32 v69, v83 offset:260
	ds_read_b32 v70, v83 offset:520
	ds_read_b32 v71, v83 offset:780
	ds_read_b32 v72, v83 offset:1040
	ds_read_b32 v73, v83 offset:1300
	ds_read_b32 v74, v83 offset:1560
	ds_read_b32 v75, v83 offset:1820
	s_waitcnt lgkmcnt(0)
	v_cvt_pk_bf16_f32 v88, v68, v69
	v_cvt_pk_bf16_f32 v89, v70, v71
	v_cvt_pk_bf16_f32 v90, v72, v73
	v_cvt_pk_bf16_f32 v91, v74, v75
	global_store_dwordx4 v13, v[88:91], s[52:53]
	s_cmp_ge_u32 s36, s56
	s_cbranch_scc1 .Lp0_r7
	s_cmpk_ge_u32 s36, 0x5b8
	s_cselect_b32 s4, 0x5b8, 0
	s_sub_u32 s5, s36, s4
	s_add_u32 s6, s5, 1152
	s_sub_u32 s7, s5, 8
	s_cmpk_lt_u32 s5, 0x138
	s_cselect_b32 s7, s6, s7
	s_cmpk_lt_u32 s5, 0x130
	s_cselect_b32 s7, s5, s7
	s_add_u32 s58, s7, s4
	s_cmpk_ge_u32 s58, 0x5b8
	s_cselect_b32 s30, 1, 0
	s_mul_i32 s4, s30, 0x5b8
	s_sub_u32 s31, s58, s4
	s_cmpk_lt_u32 s31, 0x130
	s_cbranch_scc1 .Lp0_dec10_win
	s_cmpk_lt_u32 s31, 0x1b0
	s_cbranch_scc1 .Lp0_dec10_wout
	s_cmpk_lt_u32 s31, 0x3b0
	s_cbranch_scc1 .Lp0_dec10_w1
	s_cmpk_lt_u32 s31, 0x5b0
	s_cbranch_scc1 .Lp0_dec10_w2
	s_sub_u32 s31, s31, 0x5b0
	s_lshr_b32 s34, s31, 2
	s_and_b32 s35, s31, 3
	v_readlane_b32 s6, v237, 51
	v_readlane_b32 s7, v237, 52
	s_mul_i32 s4, s30, 0x40000
	s_add_u32 s6, s6, s4
	s_addc_u32 s7, s7, 0
	s_add_u32 s52, s96, 0x2d80000
	s_addc_u32 s53, s97, 0
	s_mul_i32 s4, s30, 0x20000
	s_movk_i32 s50, 0x400
	s_movk_i32 s54, 0x200
	s_movk_i32 s5, 0x100
	s_branch .Lp0_dec10_join
